# attention PV section: all 15 V-fragment read pairs on a 7-quad prefetch ring (bias/S-ring regs), MFMA srcA renamed, lgkmcnt recounted
# baseline (speedup 1.0000x reference)
; #define LAS __attribute__((address_space(3)))
; __device__ __forceinline__ unsigned pk2(float lo, float hi) { return f2bf(lo) | (f2bf(hi) << 16); }
; #define MFMA16(a, b, c) __builtin_amdgcn_mfma_f32_16x16x32_bf16(a, b, c, 0, 0, 0)
; __device__ __forceinline__ v4i16_t vtr(const LAS unsigned char* p) { return __builtin_amdgcn_ds_read_tr16_b64_v4i16((LAS v4i16_t*)p); }
; __device__ __forceinline__ void attn_phase(const Params& p, LAS unsigned char* lds, const int bx, const int G, const int tid) {
;     ...
;         const int qi = 16 * wq + fr; float mx = -3e38f;
; #pragma unroll
;         for (int j = 0; j < 9; ++j)
; #pragma unroll
;             for (int e = 0; e < 4; ++e) { const int u = 16 * (wq + j) + 4 * fq + e, jk = X.nb * 64 - 64 + u, dl = u - 64 - qi; const bool ok = jk >= 0 && jk < X.n && dl >= -64 && dl <= 64;
;                 const float b = ((const LAS float*)(L + AT_BIAS))[ok ? dl + 64 : 0]; const float sv = ok ? st[j][e] + b : -1e30f; st[j][e] = sv; mx = fmaxf(mx, sv); }
;         mx = fmaxf(mx, __shfl_xor(mx, 16)); mx = fmaxf(mx, __shfl_xor(mx, 32));
;         float sm = 0.f;
; #pragma unroll
;         for (int j = 0; j < 9; ++j)
; #pragma unroll
;             for (int e = 0; e < 4; ++e) { const float pv = __expf(st[j][e] - mx); st[j][e] = pv; sm += pv; }
;         sm += __shfl_xor(sm, 16); sm += __shfl_xor(sm, 32);
;         f32x4 ot[4];
; #pragma unroll
;         for (int dt = 0; dt < 4; ++dt) ot[dt] = (f32x4){0.f, 0.f, 0.f, 0.f};
; #pragma unroll
;         for (int ks = 0; ks < 5; ++ks) { v4u pw; pw.x = pk2(st[2 * ks][0], st[2 * ks][1]); pw.y = pk2(st[2 * ks][2], st[2 * ks][3]); pw.z = pk2(st[2 * ks + 1][0], st[2 * ks + 1][1]); pw.w = pk2(st[2 * ks + 1][2], st[2 * ks + 1][3]);
;             const bf16x8 pb = __builtin_bit_cast(bf16x8, pw);
; #pragma unroll
;             for (int dt = 0; dt < 4; ++dt) { const LAS unsigned char* vr = vbp + ks * 5120 + dt * 32;
;                 const v4i16_t lo = vtr(vr), hi = vtr(vr + 16 * 160);
;                 ot[dt] = MFMA16(__builtin_shufflevector(lo, hi, 0, 1, 2, 3, 4, 5, 6, 7), pb, ot[dt]); } }
.LBB0_487:
	s_or_b64 exec, exec, s[12:13]
	s_mov_b32 s2, 0xff61b1e6
	v_max3_f32 v60, v66, s2, v65
	v_max3_f32 v60, v60, v96, v67
	v_max3_f32 v60, v60, v98, v97
	v_max3_f32 v60, v60, v93, v92
	v_max3_f32 v60, v60, v95, v94
	v_max3_f32 v60, v60, v89, v88
	v_max3_f32 v60, v60, v91, v90
	v_max3_f32 v60, v60, v85, v84
	v_max3_f32 v60, v60, v87, v86
	v_max3_f32 v60, v60, v99, v80
	v_max3_f32 v60, v60, v82, v81
	v_max3_f32 v60, v60, v83, v76
	v_max3_f32 v60, v60, v188, v187
	v_max3_f32 v60, v60, v73, v72
	v_max3_f32 v60, v60, v75, v74
	v_max3_f32 v60, v60, v190, v68
	v_max3_f32 v60, v60, v192, v191
	v_max3_f32 v60, v60, v195, v194
	ds_bpermute_b32 v62, v122, v60
	s_lshl_b32 s12, s37, 6
	s_add_i32 s13, s12, 0x7fffc000
	s_and_b32 s13, s13, 0x7ffff800
	s_and_b32 s50, s56, s86
	s_waitcnt lgkmcnt(0)
	v_max_f32_e32 v62, v62, v62
	v_max_f32_e32 v60, v60, v62
	ds_bpermute_b32 v62, v123, v60
	s_add_i32 s37, s13, 0x4000
	s_and_b32 s51, s12, 0x2000
	s_and_b64 s[12:13], s[40:41], exec
	s_cselect_b32 s13, 7, 5
	s_waitcnt lgkmcnt(0)
	v_max_f32_e32 v62, v62, v62
	v_max_f32_e32 v60, v60, v62
	v_sub_f32_e32 v63, v65, v60
	v_mul_f32_e32 v63, 0x3fb8aa3b, v63
	v_exp_f32_e32 v107, v63
	v_sub_f32_e32 v63, v96, v60
	v_mul_f32_e32 v63, 0x3fb8aa3b, v63
	v_exp_f32_e32 v96, v63
	v_sub_f32_e32 v63, v67, v60
	v_mul_f32_e32 v63, 0x3fb8aa3b, v63
	v_exp_f32_e32 v150, v63
	v_sub_f32_e32 v63, v98, v60
	v_mul_f32_e32 v63, 0x3fb8aa3b, v63
	v_exp_f32_e32 v98, v63
	v_sub_f32_e32 v63, v97, v60
	v_mul_f32_e32 v63, 0x3fb8aa3b, v63
	v_exp_f32_e32 v97, v63
	v_sub_f32_e32 v63, v93, v60
	v_mul_f32_e32 v63, 0x3fb8aa3b, v63
	v_exp_f32_e32 v151, v63
	v_sub_f32_e32 v63, v92, v60
	v_mul_f32_e32 v63, 0x3fb8aa3b, v63
	v_exp_f32_e32 v152, v63
	v_sub_f32_e32 v63, v95, v60
	v_mul_f32_e32 v63, 0x3fb8aa3b, v63
	v_exp_f32_e32 v92, v63
	v_sub_f32_e32 v63, v94, v60
	v_mul_f32_e32 v63, 0x3fb8aa3b, v63
	v_exp_f32_e32 v93, v63
	v_sub_f32_e32 v63, v89, v60
	v_sub_f32_e32 v62, v66, v60
	v_mul_f32_e32 v63, 0x3fb8aa3b, v63
	v_mul_f32_e32 v62, 0x3fb8aa3b, v62
	v_exp_f32_e32 v89, v63
	v_sub_f32_e32 v63, v88, v60
	v_exp_f32_e32 v105, v62
	v_mul_f32_e32 v63, 0x3fb8aa3b, v63
	v_exp_f32_e32 v88, v63
	v_sub_f32_e32 v63, v91, v60
	v_mul_f32_e32 v63, 0x3fb8aa3b, v63
	v_exp_f32_e32 v91, v63
	v_sub_f32_e32 v63, v90, v60
	v_add_f32_e32 v62, 0, v105
	v_mul_f32_e32 v63, 0x3fb8aa3b, v63
	v_add_f32_e32 v62, v107, v62
	v_exp_f32_e32 v90, v63
	v_sub_f32_e32 v63, v85, v60
	v_add_f32_e32 v62, v96, v62
	v_mul_f32_e32 v63, 0x3fb8aa3b, v63
	v_add_f32_e32 v62, v150, v62
	v_exp_f32_e32 v85, v63
	v_sub_f32_e32 v63, v84, v60
	v_add_f32_e32 v62, v98, v62
	v_mul_f32_e32 v63, 0x3fb8aa3b, v63
	v_add_f32_e32 v62, v97, v62
	v_exp_f32_e32 v196, v63
	v_sub_f32_e32 v63, v87, v60
	v_add_f32_e32 v62, v151, v62
	v_mul_f32_e32 v63, 0x3fb8aa3b, v63
	v_add_f32_e32 v62, v152, v62
	v_exp_f32_e32 v77, v63
	v_sub_f32_e32 v63, v86, v60
	v_add_f32_e32 v62, v92, v62
	v_mul_f32_e32 v63, 0x3fb8aa3b, v63
	v_bfe_u32 v87, v97, 16, 1
	v_bfe_u32 v95, v107, 16, 1
	v_add_f32_e32 v62, v93, v62
	v_exp_f32_e32 v79, v63
	v_sub_f32_e32 v63, v99, v60
	v_add3_u32 v99, v107, v95, s33
	v_add3_u32 v87, v97, v87, s33
	v_bfe_u32 v95, v105, 16, 1
	v_bfe_u32 v97, v96, 16, 1
	v_bfe_u32 v107, v98, 16, 1
	v_add_f32_e32 v62, v89, v62
	v_bfe_u32 v94, v150, 16, 1
	v_add3_u32 v98, v98, v107, s33
	v_add3_u32 v96, v96, v97, s33
	v_add3_u32 v95, v105, v95, s33
	v_add_f32_e32 v62, v88, v62
	v_add3_u32 v94, v150, v94, s33
	v_bfe_u32 v150, v151, 16, 1
	v_lshrrev_b32_e32 v105, 16, v95
	v_lshrrev_b32_e32 v95, 16, v96
	v_lshrrev_b32_e32 v96, 16, v98
	v_add_f32_e32 v62, v91, v62
	v_bfe_u32 v86, v152, 16, 1
	v_add3_u32 v150, v151, v150, s33
	v_and_or_b32 v96, v87, s11, v96
	v_and_or_b32 v95, v94, s11, v95
	v_and_or_b32 v94, v99, s11, v105
	v_bfe_u32 v87, v90, 16, 1
	v_bfe_u32 v98, v88, 16, 1
	v_bfe_u32 v99, v93, 16, 1
	v_add_f32_e32 v62, v90, v62
	v_add3_u32 v86, v152, v86, s33
	v_lshrrev_b32_e32 v97, 16, v150
	ds_read_b64_tr_b16 v[152:153], v186 offset:30208
	ds_read_b64_tr_b16 v[150:151], v186 offset:27648
	ds_read_b64_tr_b16 v[198:199], v186 offset:27680
	ds_read_b64_tr_b16 v[200:201], v186 offset:30240
	v_add3_u32 v93, v93, v99, s33
	v_add3_u32 v98, v88, v98, s33
	v_add3_u32 v87, v90, v87, s33
	v_bfe_u32 v88, v92, 16, 1
	v_bfe_u32 v90, v89, 16, 1
	v_bfe_u32 v99, v91, 16, 1
	v_bfe_u32 v105, v85, 16, 1
	v_add_f32_e32 v62, v85, v62
	v_and_or_b32 v97, v86, s11, v97
	v_add3_u32 v91, v91, v99, s33
	v_add3_u32 v89, v89, v90, s33
	v_add3_u32 v88, v92, v88, s33
	v_lshrrev_b32_e32 v90, 16, v88
	v_lshrrev_b32_e32 v92, 16, v89
	v_lshrrev_b32_e32 v88, 16, v91
	ds_read_b64_tr_b16 v[202:203], v186 offset:27712
	ds_read_b64_tr_b16 v[204:205], v186 offset:30272
	ds_read_b64_tr_b16 v[206:207], v186 offset:27744
	ds_read_b64_tr_b16 v[208:209], v186 offset:30304
	v_cvt_pk_bf16_f32 v89, v85, v196
	v_and_or_b32 v88, v87, s11, v88
	v_and_or_b32 v87, v98, s11, v92
	v_and_or_b32 v86, v93, s11, v90
	ds_read_b64_tr_b16 v[90:91], v186 offset:32768
	ds_read_b64_tr_b16 v[92:93], v186 offset:35328
	ds_read_b64_tr_b16 v[236:237], v186 offset:32800
	ds_read_b64_tr_b16 v[238:239], v186 offset:35360
	ds_read_b64_tr_b16 v[246:247], v186 offset:32832
	ds_read_b64_tr_b16 v[248:249], v186 offset:35392
	ds_read_b64_tr_b16 v[210:211], v186 offset:32864
	ds_read_b64_tr_b16 v[212:213], v186 offset:35424
	s_waitcnt lgkmcnt(14)
	v_mfma_f32_16x16x32_bf16 v[150:153], v[150:153], v[94:97], 0
	v_mul_f32_e32 v63, 0x3fb8aa3b, v63
	v_exp_f32_e32 v78, v63
	v_sub_f32_e32 v63, v80, v60
	s_waitcnt lgkmcnt(6)
; #define LAS __attribute__((address_space(3)))
; __device__ __forceinline__ unsigned pk2(float lo, float hi) { return f2bf(lo) | (f2bf(hi) << 16); }
; #define MFMA16(a, b, c) __builtin_amdgcn_mfma_f32_16x16x32_bf16(a, b, c, 0, 0, 0)
; __device__ __forceinline__ v4i16_t vtr(const LAS unsigned char* p) { return __builtin_amdgcn_ds_read_tr16_b64_v4i16((LAS v4i16_t*)p); }
; __device__ __forceinline__ void attn_phase(const Params& p, LAS unsigned char* lds, const int bx, const int G, const int tid) {
;     ...
;             for (int e = 0; e < 4; ++e) { const float pv = __expf(st[j][e] - mx); st[j][e] = pv; sm += pv; }
;         sm += __shfl_xor(sm, 16); sm += __shfl_xor(sm, 32);
;         f32x4 ot[4];
; #pragma unroll
;         for (int dt = 0; dt < 4; ++dt) ot[dt] = (f32x4){0.f, 0.f, 0.f, 0.f};
; #pragma unroll
;         for (int ks = 0; ks < 5; ++ks) { v4u pw; pw.x = pk2(st[2 * ks][0], st[2 * ks][1]); pw.y = pk2(st[2 * ks][2], st[2 * ks][3]); pw.z = pk2(st[2 * ks + 1][0], st[2 * ks + 1][1]); pw.w = pk2(st[2 * ks + 1][2], st[2 * ks + 1][3]);
;             const bf16x8 pb = __builtin_bit_cast(bf16x8, pw);
; #pragma unroll
;             for (int dt = 0; dt < 4; ++dt) { const LAS unsigned char* vr = vbp + ks * 5120 + dt * 32;
;                 const v4i16_t lo = vtr(vr), hi = vtr(vr + 16 * 160);
;                 ot[dt] = MFMA16(__builtin_shufflevector(lo, hi, 0, 1, 2, 3, 4, 5, 6, 7), pb, ot[dt]); } }
	v_mfma_f32_16x16x32_bf16 v[90:93], v[90:93], v[86:89], v[150:153]
	s_nop 2
	ds_read_b64_tr_b16 v[214:215], v186 offset:37888
	ds_read_b64_tr_b16 v[216:217], v186 offset:40448
	v_mul_f32_e32 v63, 0x3fb8aa3b, v63
	v_exp_f32_e32 v80, v63
	v_mfma_f32_16x16x32_bf16 v[198:201], v[198:201], v[94:97], 0
	v_sub_f32_e32 v63, v82, v60
	v_mul_f32_e32 v63, 0x3fb8aa3b, v63
	v_exp_f32_e32 v82, v63
	s_waitcnt lgkmcnt(6)
	v_mfma_f32_16x16x32_bf16 v[150:153], v[236:239], v[86:89], v[198:201]
	s_nop 2
	ds_read_b64_tr_b16 v[218:219], v186 offset:37920
	ds_read_b64_tr_b16 v[220:221], v186 offset:40480
	v_sub_f32_e32 v63, v81, v60
	v_mul_f32_e32 v63, 0x3fb8aa3b, v63
	v_mfma_f32_16x16x32_bf16 v[202:205], v[202:205], v[94:97], 0
	v_exp_f32_e32 v81, v63
	v_sub_f32_e32 v63, v83, v60
	v_add_f32_e32 v62, v196, v62
	v_mul_f32_e32 v63, 0x3fb8aa3b, v63
	s_waitcnt lgkmcnt(6)
	v_mfma_f32_16x16x32_bf16 v[198:201], v[246:249], v[86:89], v[202:205]
	s_nop 2
	ds_read_b64_tr_b16 v[222:223], v186 offset:37952
	ds_read_b64_tr_b16 v[224:225], v186 offset:40512
	v_add_f32_e32 v62, v77, v62
	v_exp_f32_e32 v83, v63
	v_sub_f32_e32 v63, v76, v60
	v_mfma_f32_16x16x32_bf16 v[94:97], v[206:209], v[94:97], 0
	v_add_f32_e32 v62, v79, v62
	v_mul_f32_e32 v63, 0x3fb8aa3b, v63
	v_add_f32_e32 v62, v78, v62
	v_exp_f32_e32 v84, v63
	v_add_f32_e32 v62, v80, v62
	v_add_f32_e32 v62, v82, v62
	s_waitcnt lgkmcnt(6)
	v_mfma_f32_16x16x32_bf16 v[86:89], v[210:213], v[86:89], v[94:97]
	ds_read_b64_tr_b16 v[226:227], v186 offset:37984
	ds_read_b64_tr_b16 v[228:229], v186 offset:40544
	v_add_f32_e32 v62, v81, v62
	v_sub_f32_e32 v63, v188, v60
	v_add_f32_e32 v62, v83, v62
	v_bfe_u32 v94, v81, 16, 1
	v_bfe_u32 v95, v80, 16, 1
	v_bfe_u32 v96, v79, 16, 1
	v_add3_u32 v96, v79, v96, s33
	v_add3_u32 v79, v80, v95, s33
	v_add3_u32 v80, v81, v94, s33
	v_bfe_u32 v94, v82, 16, 1
	v_bfe_u32 v95, v83, 16, 1
	v_mul_f32_e32 v63, 0x3fb8aa3b, v63
	v_bfe_u32 v85, v84, 16, 1
	v_add3_u32 v83, v83, v95, s33
	v_add3_u32 v82, v82, v94, s33
	v_add_f32_e32 v62, v84, v62
	v_exp_f32_e32 v69, v63
	v_sub_f32_e32 v63, v187, v60
	v_add3_u32 v81, v84, v85, s33
	v_bfe_u32 v84, v77, 16, 1
	v_bfe_u32 v85, v78, 16, 1
	v_lshrrev_b32_e32 v82, 16, v82
	v_lshrrev_b32_e32 v83, 16, v83
	v_mul_f32_e32 v63, 0x3fb8aa3b, v63
	v_add3_u32 v78, v78, v85, s33
	v_add3_u32 v77, v77, v84, s33
	v_and_or_b32 v81, v81, s11, v83
	v_and_or_b32 v80, v80, s11, v82
	ds_read_b64_tr_b16 v[236:237], v186 offset:43008
	ds_read_b64_tr_b16 v[238:239], v186 offset:45568
	v_exp_f32_e32 v71, v63
	v_sub_f32_e32 v63, v73, v60
	v_mul_f32_e32 v63, 0x3fb8aa3b, v63
	v_exp_f32_e32 v70, v63
	v_sub_f32_e32 v63, v72, v60
	v_lshrrev_b32_e32 v77, 16, v77
	v_lshrrev_b32_e32 v78, 16, v78
	v_mul_f32_e32 v63, 0x3fb8aa3b, v63
	v_and_or_b32 v79, v79, s11, v78
	v_and_or_b32 v78, v96, s11, v77
	v_exp_f32_e32 v73, v63
	v_sub_f32_e32 v63, v75, v60
	s_waitcnt lgkmcnt(8)
	v_mfma_f32_16x16x32_bf16 v[82:85], v[214:217], v[78:81], v[90:93]
	s_nop 2
	ds_read_b64_tr_b16 v[246:247], v186 offset:43040
	ds_read_b64_tr_b16 v[248:249], v186 offset:45600
	v_mul_f32_e32 v63, 0x3fb8aa3b, v63
	v_exp_f32_e32 v72, v63
	v_sub_f32_e32 v63, v74, v60
	v_mul_f32_e32 v63, 0x3fb8aa3b, v63
	v_exp_f32_e32 v75, v63
	v_sub_f32_e32 v63, v190, v60
	v_mul_f32_e32 v63, 0x3fb8aa3b, v63
	s_waitcnt lgkmcnt(8)
	v_mfma_f32_16x16x32_bf16 v[90:93], v[218:221], v[78:81], v[150:153]
	ds_read_b64_tr_b16 v[210:211], v186 offset:43072
	ds_read_b64_tr_b16 v[212:213], v186 offset:45632
	s_nop 0
	ds_read_b64_tr_b16 v[214:215], v186 offset:43104
	ds_read_b64_tr_b16 v[216:217], v186 offset:45664
	v_add_f32_e32 v62, v69, v62
	v_exp_f32_e32 v74, v63
	v_sub_f32_e32 v63, v68, v60
	v_add_f32_e32 v62, v71, v62
	v_mul_f32_e32 v63, 0x3fb8aa3b, v63
	v_add_f32_e32 v62, v70, v62
	v_exp_f32_e32 v76, v63
	v_add_f32_e32 v62, v73, v62
	v_add_f32_e32 v62, v72, v62
	s_waitcnt lgkmcnt(10)
	v_mfma_f32_16x16x32_bf16 v[94:97], v[222:225], v[78:81], v[198:201]
	v_add_f32_e32 v62, v75, v62
	v_add_f32_e32 v62, v74, v62
	v_bfe_u32 v77, v76, 16, 1
	s_waitcnt lgkmcnt(8)
	v_mfma_f32_16x16x32_bf16 v[78:81], v[226:229], v[78:81], v[86:89]
	v_add_f32_e32 v62, v76, v62
	v_sub_f32_e32 v63, v192, v60
	v_mul_f32_e32 v63, 0x3fb8aa3b, v63
	v_bfe_u32 v86, v75, 16, 1
	v_bfe_u32 v87, v73, 16, 1
	v_bfe_u32 v88, v71, 16, 1
	v_add3_u32 v88, v71, v88, s33
	v_add3_u32 v71, v73, v87, s33
	v_bfe_u32 v87, v74, 16, 1
	v_add3_u32 v74, v74, v87, s33
	v_add3_u32 v73, v76, v77, s33
	v_bfe_u32 v76, v69, 16, 1
	v_bfe_u32 v77, v70, 16, 1
	v_lshrrev_b32_e32 v74, 16, v74
	v_add3_u32 v70, v70, v77, s33
	v_add3_u32 v69, v69, v76, s33
	v_and_or_b32 v73, v73, s11, v74
	v_cvt_pk_bf16_f32 v72, v72, v75
	ds_read_b64_tr_b16 v[218:219], v186 offset:48128
	ds_read_b64_tr_b16 v[220:221], v186 offset:50688
	v_lshrrev_b32_e32 v69, 16, v69
	v_lshrrev_b32_e32 v70, 16, v70
	v_and_or_b32 v71, v71, s11, v70
	v_and_or_b32 v70, v88, s11, v69
	v_exp_f32_e32 v66, v63
	v_sub_f32_e32 v63, v191, v60
	s_waitcnt lgkmcnt(8)
; #define LAS __attribute__((address_space(3)))
; __device__ __forceinline__ unsigned pk2(float lo, float hi) { return f2bf(lo) | (f2bf(hi) << 16); }
; #define MFMA16(a, b, c) __builtin_amdgcn_mfma_f32_16x16x32_bf16(a, b, c, 0, 0, 0)
; __device__ __forceinline__ v4i16_t vtr(const LAS unsigned char* p) { return __builtin_amdgcn_ds_read_tr16_b64_v4i16((LAS v4i16_t*)p); }
; __device__ __forceinline__ void attn_phase(const Params& p, LAS unsigned char* lds, const int bx, const int G, const int tid) {
;     ...
;         for (int ks = 0; ks < 5; ++ks) { v4u pw; pw.x = pk2(st[2 * ks][0], st[2 * ks][1]); pw.y = pk2(st[2 * ks][2], st[2 * ks][3]); pw.z = pk2(st[2 * ks + 1][0], st[2 * ks + 1][1]); pw.w = pk2(st[2 * ks + 1][2], st[2 * ks + 1][3]);
;             const bf16x8 pb = __builtin_bit_cast(bf16x8, pw);
; #pragma unroll
;             for (int dt = 0; dt < 4; ++dt) { const LAS unsigned char* vr = vbp + ks * 5120 + dt * 32;
;                 const v4i16_t lo = vtr(vr), hi = vtr(vr + 16 * 160);
;                 ot[dt] = MFMA16(__builtin_shufflevector(lo, hi, 0, 1, 2, 3, 4, 5, 6, 7), pb, ot[dt]); } }
;         { const size_t m = (size_t)(X.m0 + (X.nb * 64 + qi) * d + X.r); const float inv = 1.f / sm;
; #pragma unroll
;           for (int dt = 0; dt < 4; ++dt) { unsigned long long w = (unsigned long long)pk2(ot[dt][0] * inv, ot[dt][1] * inv) | ((unsigned long long)pk2(ot[dt][2] * inv, ot[dt][3] * inv) << 32);
	v_mfma_f32_16x16x32_bf16 v[74:77], v[236:239], v[70:73], v[82:85]
	s_nop 2
	ds_read_b64_tr_b16 v[222:223], v186 offset:48160
	ds_read_b64_tr_b16 v[224:225], v186 offset:50720
	v_mul_f32_e32 v63, 0x3fb8aa3b, v63
	v_exp_f32_e32 v65, v63
	v_sub_f32_e32 v63, v195, v60
	v_mul_f32_e32 v63, 0x3fb8aa3b, v63
	v_exp_f32_e32 v67, v63
	v_sub_f32_e32 v63, v194, v60
	s_waitcnt lgkmcnt(8)
	v_mfma_f32_16x16x32_bf16 v[82:85], v[246:249], v[70:73], v[90:93]
	ds_read_b64_tr_b16 v[226:227], v186 offset:48192
	ds_read_b64_tr_b16 v[228:229], v186 offset:50752
	s_nop 0
	ds_read_b64_tr_b16 v[236:237], v186 offset:48224
	ds_read_b64_tr_b16 v[238:239], v186 offset:50784
	v_mul_f32_e32 v63, 0x3fb8aa3b, v63
	v_exp_f32_e32 v68, v63
	v_add_f32_e32 v62, v66, v62
	v_add_f32_e32 v62, v65, v62
	v_add_f32_e32 v62, v67, v62
	s_waitcnt lgkmcnt(10)
	v_mfma_f32_16x16x32_bf16 v[86:89], v[210:213], v[70:73], v[94:97]
	v_add_f32_e32 v62, v68, v62
	ds_bpermute_b32 v63, v122, v62
	v_and_b32_sdwa v69, v67, v189 dst_sel:DWORD dst_unused:UNUSED_PAD src0_sel:WORD_1 src1_sel:DWORD
	s_waitcnt lgkmcnt(9)
	v_mfma_f32_16x16x32_bf16 v[70:73], v[214:217], v[70:73], v[78:81]
	v_add3_u32 v67, v67, v69, s33
	v_and_b32_sdwa v69, v68, v189 dst_sel:DWORD dst_unused:UNUSED_PAD src0_sel:WORD_1 src1_sel:DWORD
	v_add3_u32 v68, v68, v69, s33
	v_and_b32_sdwa v78, v66, v189 dst_sel:DWORD dst_unused:UNUSED_PAD src0_sel:WORD_1 src1_sel:DWORD
	v_add3_u32 v66, v66, v78, s33
	v_and_b32_sdwa v78, v65, v189 dst_sel:DWORD dst_unused:UNUSED_PAD src0_sel:WORD_1 src1_sel:DWORD
	v_add3_u32 v65, v65, v78, s33
	v_and_b32_e32 v68, 0xffff0000, v68
	v_and_b32_e32 v65, 0xffff0000, v65
	v_or_b32_sdwa v67, v68, v67 dst_sel:DWORD dst_unused:UNUSED_PAD src0_sel:DWORD src1_sel:WORD_1
	v_or_b32_sdwa v66, v65, v66 dst_sel:DWORD dst_unused:UNUSED_PAD src0_sel:DWORD src1_sel:WORD_1
	v_mov_b32_e32 v68, v0
	v_mov_b32_e32 v69, v0
	s_waitcnt lgkmcnt(0)
	v_add_f32_e32 v62, v62, v63
	ds_bpermute_b32 v63, v123, v62
	s_waitcnt lgkmcnt(1)
	v_mfma_f32_16x16x32_bf16 v[74:77], v[218:221], v[66:69], v[74:77]
	v_sub_u32_e32 v61, s13, v3
	s_cselect_b32 s12, s51, s37
	v_lshrrev_b32_e64 v61, v61, s50
	s_waitcnt lgkmcnt(0)
	v_mfma_f32_16x16x32_bf16 v[78:81], v[222:225], v[66:69], v[82:85]
	s_nop 2
	v_add_f32_e32 v62, v62, v63
	v_or_b32_e32 v63, v64, v121
	v_or_b32_e32 v61, s12, v61
	v_lshl_add_u32 v61, v63, v3, v61
	v_div_scale_f32 v3, s[12:13], v62, v62, 1.0
	v_rcp_f32_e32 v63, v3
	s_waitcnt lgkmcnt(0)
	v_mfma_f32_16x16x32_bf16 v[82:85], v[226:229], v[66:69], v[86:89]
	s_nop 2
	v_mov_b32_e32 v107, v0
	v_fma_f32 v64, -v3, v63, 1.0
	v_fmac_f32_e32 v63, v64, v63
	v_div_scale_f32 v64, vcc, 1.0, v62, 1.0
	v_mul_f32_e32 v65, v64, v63
	s_waitcnt lgkmcnt(0)
	v_mfma_f32_16x16x32_bf16 v[66:69], v[236:239], v[66:69], v[70:73]
	v_readlane_b32 s2, v254, 55
	v_readlane_b32 s3, v254, 56
	s_nop 0
	v_fma_f32 v70, -v3, v65, v64
	v_fmac_f32_e32 v65, v70, v63
	v_fma_f32 v3, -v3, v65, v64
	v_div_fmas_f32 v3, v3, v63, v65
	v_div_fixup_f32 v3, v3, v62, 1.0
	v_mov_b64_e32 v[64:65], s[90:91]
	v_lshlrev_b32_e32 v70, 6, v2
	v_mad_i64_i32 v[64:65], s[12:13], v61, s57, v[64:65]
	v_ashrrev_i32_e32 v71, 31, v70
	v_mul_f32_e32 v63, v3, v74
	v_lshl_add_u64 v[64:65], v[70:71], 1, v[64:65]
	v_mul_f32_e32 v70, v3, v75
	v_bfe_u32 v71, v63, 16, 1
	v_cvt_pk_bf16_f32 v70, v63, v70
	v_mul_f32_e32 v63, v3, v76
	v_mul_f32_e32 v71, v3, v77
	v_lshl_add_u64 v[64:65], v[64:65], 0, v[106:107]
	v_cvt_pk_bf16_f32 v71, v63, v71
	v_mul_f32_e32 v63, v3, v78
	global_store_dwordx2 v[64:65], v[70:71], off
	v_mul_f32_e32 v70, v3, v79
	v_cvt_pk_bf16_f32 v70, v63, v70
	v_mul_f32_e32 v63, v3, v80
	v_mul_f32_e32 v71, v3, v81
	v_cvt_pk_bf16_f32 v71, v63, v71
	v_mul_f32_e32 v63, v3, v82
	global_store_dwordx2 v[64:65], v[70:71], off offset:32
	v_mul_f32_e32 v70, v3, v83
	v_cvt_pk_bf16_f32 v70, v63, v70
	v_mul_f32_e32 v63, v3, v84
	v_mul_f32_e32 v71, v3, v85
	v_bfe_u32 v72, v71, 16, 1
	v_cvt_pk_bf16_f32 v71, v63, v71
	v_mul_f32_e32 v63, v3, v66
	v_mul_f32_e32 v66, v3, v67
	v_cvt_pk_bf16_f32 v66, v63, v66
	v_mul_f32_e32 v63, v3, v68
	v_mul_f32_e32 v3, v3, v69
	v_bfe_u32 v67, v63, 16, 1
	v_add3_u32 v63, v63, v67, s33
	v_bfe_u32 v67, v3, 16, 1
	v_lshrrev_b32_e32 v63, 16, v63
	v_add3_u32 v3, v3, v67, s33
	v_and_or_b32 v67, v3, s11, v63
	global_store_dwordx2 v[64:65], v[70:71], off offset:64
	global_store_dwordx2 v[64:65], v[66:67], off offset:96
	s_and_saveexec_b64 s[12:13], s[2:3]
	s_cbranch_execz .LBB0_386
	s_mov_b32 s37, 0x800000
	v_cmp_gt_f32_e32 vcc, s37, v62
	s_mov_b32 s37, 0x3f317217
	s_mov_b32 s2, 0x7f800000
	v_cndmask_b32_e64 v3, 0, 32, vcc
	v_ldexp_f32 v3, v62, v3
	v_log_f32_e32 v3, v3
	v_cndmask_b32_e32 v62, 0, v233, vcc
	v_mul_f32_e32 v63, 0x3f317217, v3
	v_fma_f32 v63, v3, s37, -v63
	v_fmac_f32_e32 v63, 0x3377d1cf, v3
	v_fmac_f32_e32 v63, 0x3f317217, v3
	v_cmp_lt_f32_e64 vcc, |v3|, s2
	v_readlane_b32 s2, v253, 7
	v_readlane_b32 s3, v253, 8
	v_cndmask_b32_e32 v3, v3, v63, vcc
	v_sub_f32_e32 v3, v3, v62
	v_add_f32_e32 v62, v60, v3
	v_ashrrev_i32_e32 v3, 31, v2
	v_mad_i64_i32 v[60:61], s[40:41], v61, 48, s[2:3]
	v_lshl_add_u64 v[2:3], v[2:3], 2, v[60:61]
	global_store_dword v[2:3], v62, off
	s_branch .LBB0_386
